# acquire invalidate also moved to the arrive of the two split grid barriers (P3 / P5), on top of the early invalidate at the counter polls
# baseline (speedup 1.0000x reference)
; #define LAS __attribute__((address_space(3)))
; __device__ __forceinline__ unsigned xb_add(unsigned* p, unsigned v) { return __hip_atomic_fetch_add(p, v, __ATOMIC_RELAXED, __HIP_MEMORY_SCOPE_AGENT); }
; __device__ __forceinline__ void xcd_barrier_arrive(const XcdBarrier& b, volatile LAS unsigned* genw) {
;     asm volatile("s_waitcnt vmcnt(0)" ::: "memory");
;     __syncthreads();
;     if (threadIdx.x == 0) {
;         unsigned* bar = b.bar;
;         __builtin_amdgcn_s_waitcnt(0);
;         unsigned nloc = b.st[0], nx = b.st[1];
;         if (nloc == 0u) { xcd_barrier_complete(bar, b.x, nloc, nx); b.st[0] = nloc; b.st[1] = nx; }
;         const unsigned old = xb_add(&bar[XB_XSUB(b.x)], 1u);
;         const unsigned gen = old / nloc;
;         if (old + 1u == (gen + 1u) * nloc) {
.LBB0_282:
	s_mov_b64 s[6:7], exec
	v_mbcnt_lo_u32_b32 v1, s6, 0
	v_mbcnt_hi_u32_b32 v1, s7, v1
	v_cmp_eq_u32_e32 vcc, 0, v1
	s_and_saveexec_b64 s[4:5], vcc
	s_cbranch_execz .LBB0_284
	s_lshl_b32 s3, s54, 8
	s_add_u32 s8, s90, s3
	s_addc_u32 s9, s91, 0
	s_bcnt1_i32_b64 s3, s[6:7]
	v_mov_b32_e32 v4, 0x1000
	v_mov_b32_e32 v5, s3
	global_atomic_add v4, v4, v5, s[8:9] offset:1024 sc0
	buffer_inv sc1

; #define LAS __attribute__((address_space(3)))
; __device__ __forceinline__ unsigned xb_ld(unsigned* p)              { return __hip_atomic_load(p, __ATOMIC_RELAXED, __HIP_MEMORY_SCOPE_AGENT); }
; #define XB_SPIN(cond, bar) do { unsigned _sp = 0; while (cond) { __builtin_amdgcn_s_sleep(1); \
;     if ((++_sp & 255u) == 0u) { if (xb_ld(&(bar)[XB_TMO])) break; if (_sp > XB_SPIN_CAP) { atomicAdd(&(bar)[XB_TMO], 1u); break; } } } } while (0)
; __device__ __forceinline__ void xcd_barrier_wait(const XcdBarrier& b, volatile LAS unsigned* genw) {
;     __syncthreads();
;     if (threadIdx.x == 0) {
;         unsigned* bar = b.bar; const unsigned gen = *genw;
;         XB_SPIN(xb_ld(&bar[XB_XGEN(b.x)]) == gen, bar);
;         __builtin_amdgcn_fence(__ATOMIC_ACQUIRE, "agent");
;         asm volatile("s_waitcnt vmcnt(0)" ::: "memory");
;     }
;     __syncthreads();
.LBB0_371:
	s_or_b64 exec, exec, s[4:5]
.LBB0_372:
	s_waitcnt vmcnt(0)
	s_waitcnt vmcnt(0)
.LBB0_373:
	s_or_b64 exec, exec, s[0:1]
	s_barrier

; #define LAS __attribute__((address_space(3)))
; __device__ __forceinline__ unsigned xb_add(unsigned* p, unsigned v) { return __hip_atomic_fetch_add(p, v, __ATOMIC_RELAXED, __HIP_MEMORY_SCOPE_AGENT); }
; __device__ __forceinline__ void xcd_barrier_arrive(const XcdBarrier& b, volatile LAS unsigned* genw) {
;     asm volatile("s_waitcnt vmcnt(0)" ::: "memory");
;     __syncthreads();
;     if (threadIdx.x == 0) {
;         unsigned* bar = b.bar;
;         __builtin_amdgcn_s_waitcnt(0);
;         unsigned nloc = b.st[0], nx = b.st[1];
;         if (nloc == 0u) { xcd_barrier_complete(bar, b.x, nloc, nx); b.st[0] = nloc; b.st[1] = nx; }
;         const unsigned old = xb_add(&bar[XB_XSUB(b.x)], 1u);
;         const unsigned gen = old / nloc;
;         if (old + 1u == (gen + 1u) * nloc) {
.LBB0_396:
	s_mov_b64 s[6:7], exec
	v_mbcnt_lo_u32_b32 v2, s6, 0
	v_mbcnt_hi_u32_b32 v2, s7, v2
	v_cmp_eq_u32_e32 vcc, 0, v2
	s_and_saveexec_b64 s[4:5], vcc
	s_cbranch_execz .LBB0_398
	s_lshl_b32 s3, s54, 8
	s_add_u32 s8, s90, s3
	s_addc_u32 s9, s91, 0
	s_bcnt1_i32_b64 s3, s[6:7]
	v_mov_b32_e32 v5, 0x1000
	v_mov_b32_e32 v6, s3
	global_atomic_add v5, v5, v6, s[8:9] offset:1024 sc0
	buffer_inv sc1

; #define LAS __attribute__((address_space(3)))
; __device__ __forceinline__ unsigned xb_ld(unsigned* p)              { return __hip_atomic_load(p, __ATOMIC_RELAXED, __HIP_MEMORY_SCOPE_AGENT); }
; #define XB_SPIN(cond, bar) do { unsigned _sp = 0; while (cond) { __builtin_amdgcn_s_sleep(1); \
;     if ((++_sp & 255u) == 0u) { if (xb_ld(&(bar)[XB_TMO])) break; if (_sp > XB_SPIN_CAP) { atomicAdd(&(bar)[XB_TMO], 1u); break; } } } } while (0)
; __device__ __forceinline__ void xcd_barrier_wait(const XcdBarrier& b, volatile LAS unsigned* genw) {
;     __syncthreads();
;     if (threadIdx.x == 0) {
;         unsigned* bar = b.bar; const unsigned gen = *genw;
;         XB_SPIN(xb_ld(&bar[XB_XGEN(b.x)]) == gen, bar);
;         __builtin_amdgcn_fence(__ATOMIC_ACQUIRE, "agent");
;         asm volatile("s_waitcnt vmcnt(0)" ::: "memory");
;     }
;     __syncthreads();
.LBB0_459:
	s_or_b64 exec, exec, s[4:5]
.LBB0_460:
	s_waitcnt vmcnt(0)
	s_waitcnt vmcnt(0)
.LBB0_461:
	s_or_b64 exec, exec, s[0:1]
	s_barrier
